# grid barrier skips the L2 write-back after phases whose stores are all write-through (LN1, mlp1, LN2); idle-WG conversion stores made sc1
# speedup vs baseline: 1.0089x; 1.0056x over previous
.LBB0_53:
	s_andn2_saveexec_b64 s[8:9], s[22:23]
	s_cbranch_execz .LBB0_73
	s_mov_b64 s[22:23], exec
	v_readlane_b32 s5, v255, 44
	s_cmp_lt_i32 s5, 2
	s_cbranch_scc0 .Lbar_skip_wb
	buffer_wbl2 sc1
.Lbar_skip_wb:
	s_waitcnt lgkmcnt(0)
	s_waitcnt vmcnt(0)
	v_mbcnt_lo_u32_b32 v0, s22, 0
	v_mbcnt_hi_u32_b32 v0, s23, v0
	v_cmp_eq_u32_e32 vcc, 0, v0
	s_and_saveexec_b64 s[26:27], vcc
	s_cbranch_execz .LBB0_56
	s_bcnt1_i32_b64 s5, s[22:23]
	v_readlane_b32 s8, v254, 29
	v_mov_b32_e32 v3, s5
	v_readlane_b32 s9, v254, 30
	s_nop 4
	global_atomic_add v3, v1, v3, s[8:9] sc0
